# baseline (speedup 1.0000x reference)
; __device__ __forceinline__ unsigned cvt_pk_bf16(float lo, float hi) { unsigned r; asm volatile("v_cvt_pk_bf16_f32 %0, %1, %2" : "=v"(r) : "v"(lo), "v"(hi)); return r; }
; #define GAS __attribute__((address_space(1)))
;     __device__ __forceinline__ void operator()(const f32x4 (&acc)[2][2][4][2], const Unit& u, int wr, int wc, int fr, int fq) const {
;         const int g = u.pm >> 7; const int smask = g ? 4095 : 2047;
;         const int row0 = (u.pm & 127) * 256 + wr * 64 + fr;
;         const bool isq = u.pn < 2;
;         bf16_t* base = (bf16_t*)((g ? B1 : B0) + (isq ? GB_MIX : GB_K)); const int pitch = isq ? MIXW : 512; const int colt = isq ? u.pn * 256 : (u.pn - 2) * 256;
;         const float qs = isq ? 0.125f * 1.4426950408889634f : 1.f;
;         const int col0 = colt + wc * 32 + 8 * fq;
;         const int ub = 8 * (wc & 1) + 2 * fq;
; #pragma unroll
;         for (int ai = 0; ai < 2; ++ai)
; #pragma unroll
;             for (int m = 0; m < 4; ++m) {
;                 const int row = row0 + ai * 128 + m * 16;
;                 const float rs = rsl[u.ord * 256 + wr * 64 + fr + ai * 128 + m * 16] * qs;
;                 const int pos = row & smask;
;                 const f32x4 t0 = *(const GAS f32x4*)(rope + pos * 16 + ub), t1 = *(const GAS f32x4*)(rope + pos * 16 + ub + 1);
;                 bf16_t* rowp = base + (size_t)row * pitch + col0;
; #pragma unroll
;                 for (int bj = 0; bj < 2; ++bj) {
;                     const f32x4 v0 = acc[ai][bj][m][0], v1 = acc[ai][bj][m][1];
;                     const float a0 = (v0[0] * t0[0] - v0[1] * t0[1]) * rs, a1 = (v0[1] * t0[0] + v0[0] * t0[1]) * rs;
;                     const float a2 = (v0[2] * t0[2] - v0[3] * t0[3]) * rs, a3 = (v0[3] * t0[2] + v0[2] * t0[3]) * rs;
;                     const float b0 = (v1[0] * t1[0] - v1[1] * t1[1]) * rs, b1 = (v1[1] * t1[0] + v1[0] * t1[1]) * rs;
;                     const float b2 = (v1[2] * t1[2] - v1[3] * t1[3]) * rs, b3 = (v1[3] * t1[2] + v1[2] * t1[3]) * rs;
;                     u32x4 w; w.x = cvt_pk_bf16(a0, a1); w.y = cvt_pk_bf16(a2, a3); w.z = cvt_pk_bf16(b0, b1); w.w = cvt_pk_bf16(b2, b3);
;                     *(GAS u32x4*)(rowp + bj * 128) = w;
.LBB0_379:
	s_lshl_b32 s13, s76, 8
	s_and_b32 s19, s13, 0x7f00
	s_cmpk_lt_u32 s76, 0x80
	s_movk_i32 s13, 0x7ff
	s_cselect_b32 s13, s13, 0xfff
	v_add_u32_e32 v152, s19, v146
	v_and_b32_e32 v142, s13, v152
	v_lshlrev_b32_e32 v220, 8, v142
	v_lshl_add_u64 v[142:143], v[136:137], 0, v[220:221]
	v_mov_b32_e32 v223, 0
	global_load_dwordx4 v[180:183], v[142:143], off
	global_load_dwordx4 v[184:187], v[142:143], off offset:16
	v_add_u32_e32 v222, 16, v152
	v_and_b32_e32 v222, s13, v222
	v_lshlrev_b32_e32 v222, 8, v222
	v_lshl_add_u64 v[178:179], v[136:137], 0, v[222:223]
	global_load_dwordx4 v[188:191], v[178:179], off
	global_load_dwordx4 v[192:195], v[178:179], off offset:16
	v_add_u32_e32 v222, 32, v152
	v_and_b32_e32 v222, s13, v222
	v_lshlrev_b32_e32 v222, 8, v222
	v_lshl_add_u64 v[178:179], v[136:137], 0, v[222:223]
	global_load_dwordx4 v[196:199], v[178:179], off
	global_load_dwordx4 v[200:203], v[178:179], off offset:16
	v_add_u32_e32 v222, 48, v152
	v_and_b32_e32 v222, s13, v222
	v_lshlrev_b32_e32 v222, 8, v222
	v_lshl_add_u64 v[178:179], v[136:137], 0, v[222:223]
	global_load_dwordx4 v[204:207], v[178:179], off
	global_load_dwordx4 v[208:211], v[178:179], off offset:16
	v_add_u32_e32 v222, 0x80, v152
	v_and_b32_e32 v222, s13, v222
	v_lshlrev_b32_e32 v222, 8, v222
	v_lshl_add_u64 v[178:179], v[136:137], 0, v[222:223]
	global_load_dwordx4 v[212:215], v[178:179], off
	global_load_dwordx4 v[216:219], v[178:179], off offset:16
	s_cselect_b32 s30, s73, s22
	s_cselect_b32 s34, s86, s23
	s_lshl_b32 s31, s65, 8
	v_lshl_add_u32 v151, s75, 10, v149
	s_add_i32 s35, s31, 0xfffffe00
	ds_read_b32 v162, v151
	s_cmp_lt_i32 s65, 2
	s_cselect_b64 vcc, -1, 0
	v_pk_mov_b32 v[142:143], v[122:123], v[122:123] op_sel:[1,0]
	s_and_b64 s[28:29], vcc, exec
	v_bitop3_b32 v144, v152, s13, 16 bitop3:0xc8
	v_mov_b32_e32 v142, 0x3e38aa3b
	s_cselect_b32 s28, 0, 0x6000000
	s_cselect_b32 s29, s31, s35
	v_cndmask_b32_e32 v142, 1.0, v142, vcc
	v_lshlrev_b32_e32 v220, 8, v144
	s_cselect_b32 s19, s70, 0x200
	s_add_u32 s28, s30, s28
	v_or_b32_e32 v144, s29, v148
	s_addc_u32 s29, s34, 0
	v_ashrrev_i32_e32 v145, 31, v144
	v_mad_i64_i32 v[164:165], s[30:31], s19, v152, 0
	v_lshl_add_u64 v[144:145], v[144:145], 1, s[28:29]
	v_lshl_add_u64 v[164:165], v[164:165], 1, v[144:145]
	s_andn2_b64 vcc, exec, s[8:9]
	s_mov_b64 s[8:9], -1
	s_waitcnt vmcnt(8)
	v_pk_mul_f32 v[168:169], v[124:125], v[180:181]
	v_mov_b32_e32 v163, v186
	v_pk_mul_f32 v[166:167], v[126:127], v[182:183]
	v_pk_mul_f32 v[124:125], v[124:125], v[180:181] op_sel:[1,0] op_sel_hi:[0,1]
	v_pk_mul_f32 v[126:127], v[126:127], v[182:183] op_sel:[1,0] op_sel_hi:[0,1]
	v_pk_mul_f32 v[170:171], v[120:121], v[184:185]
	v_pk_mul_f32 v[120:121], v[120:121], v[184:185] op_sel:[1,0] op_sel_hi:[0,1]
	v_pk_mul_f32 v[172:173], v[122:123], v[186:187] op_sel:[1,0] op_sel_hi:[0,1]
	v_pk_mul_f32 v[174:175], v[118:119], v[182:183]
	v_pk_mul_f32 v[176:177], v[116:117], v[180:181]
	v_pk_mul_f32 v[116:117], v[116:117], v[180:181] op_sel:[1,0] op_sel_hi:[0,1]
	v_pk_mul_f32 v[118:119], v[118:119], v[182:183] op_sel:[1,0] op_sel_hi:[0,1]
	v_pk_mul_f32 v[154:155], v[114:115], v[186:187]
	v_pk_mul_f32 v[156:157], v[112:113], v[184:185]
	v_pk_mul_f32 v[112:113], v[112:113], v[184:185] op_sel:[1,0] op_sel_hi:[0,1]
	v_pk_mul_f32 v[114:115], v[114:115], v[186:187] op_sel:[1,0] op_sel_hi:[0,1]
	s_waitcnt lgkmcnt(0)
	v_pk_mul_f32 v[158:159], v[142:143], v[162:163]
	v_sub_f32_e32 v122, v168, v169
	v_add_f32_e32 v124, v124, v125
	v_sub_f32_e32 v125, v166, v167
	v_add_f32_e32 v126, v126, v127
	v_sub_f32_e32 v127, v170, v171
	v_add_f32_e32 v120, v120, v121
	v_add_f32_e32 v121, v172, v173
	v_sub_f32_e32 v143, v176, v177
	v_add_f32_e32 v116, v116, v117
	v_sub_f32_e32 v117, v174, v175
	v_add_f32_e32 v112, v112, v113
	v_sub_f32_e32 v113, v154, v155
	v_add_f32_e32 v114, v114, v115
	v_mul_f32_e32 v115, v158, v122
	v_fma_f32 v123, -v123, v187, v159
	v_add_f32_e32 v118, v118, v119
	v_sub_f32_e32 v119, v156, v157
	v_mul_f32_e32 v122, v158, v124
	v_mul_f32_e32 v124, v158, v125
	v_mul_f32_e32 v125, v158, v126
	v_mul_f32_e32 v126, v158, v127
	v_mul_f32_e32 v120, v158, v120
	v_mul_f32_e32 v121, v158, v121
	v_mul_f32_e32 v127, v158, v143
	v_mul_f32_e32 v116, v158, v116
	v_mul_f32_e32 v117, v158, v117
	v_mul_f32_e32 v143, v158, v112
	v_mul_f32_e32 v153, v158, v113
	v_mul_f32_e32 v154, v158, v114
	v_mul_f32_e32 v123, v158, v123
	v_cvt_pk_bf16_f32 v112, v115, v122
	v_cvt_pk_bf16_f32 v113, v124, v125
	v_cvt_pk_bf16_f32 v114, v126, v120
	v_cvt_pk_bf16_f32 v115, v123, v121
	v_mul_f32_e32 v118, v158, v118
	v_mul_f32_e32 v119, v158, v119
	global_store_dwordx4 v[164:165], v[112:115], off
	v_pk_mov_b32 v[120:121], v[106:107], v[106:107] op_sel:[1,0]
	v_bitop3_b32 v122, v152, s13, 32 bitop3:0xc8
	v_cvt_pk_bf16_f32 v112, v127, v116
	v_cvt_pk_bf16_f32 v113, v117, v118
	v_cvt_pk_bf16_f32 v114, v119, v143
	v_cvt_pk_bf16_f32 v115, v153, v154
	global_store_dwordx4 v[164:165], v[112:115], off offset:256
	v_add_u32_e32 v222, 0x90, v152
	v_and_b32_e32 v222, s13, v222
	v_lshlrev_b32_e32 v222, 8, v222
	v_lshl_add_u64 v[178:179], v[136:137], 0, v[222:223]
	global_load_dwordx4 v[180:183], v[178:179], off
	global_load_dwordx4 v[184:187], v[178:179], off offset:16
	v_lshl_add_u64 v[116:117], v[136:137], 0, v[220:221]
	s_nop 0
	v_or_b32_e32 v120, 16, v152
	v_mad_i64_i32 v[124:125], s[28:29], s19, v120, 0
	ds_read_b32 v120, v151 offset:64
	v_mov_b32_e32 v143, v121
	v_lshlrev_b32_e32 v220, 8, v122
	v_lshl_add_u64 v[124:125], v[124:125], 1, v[144:145]
	v_lshl_add_u64 v[122:123], v[136:137], 0, v[220:221]
	s_waitcnt vmcnt(10)
; __device__ __forceinline__ unsigned cvt_pk_bf16(float lo, float hi) { unsigned r; asm volatile("v_cvt_pk_bf16_f32 %0, %1, %2" : "=v"(r) : "v"(lo), "v"(hi)); return r; }
; #define GAS __attribute__((address_space(1)))
;     __device__ __forceinline__ void operator()(const f32x4 (&acc)[2][2][4][2], const Unit& u, int wr, int wc, int fr, int fq) const {
;     ...
;                 const int row = row0 + ai * 128 + m * 16;
;                 const float rs = rsl[u.ord * 256 + wr * 64 + fr + ai * 128 + m * 16] * qs;
;                 const int pos = row & smask;
;                 const f32x4 t0 = *(const GAS f32x4*)(rope + pos * 16 + ub), t1 = *(const GAS f32x4*)(rope + pos * 16 + ub + 1);
;                 bf16_t* rowp = base + (size_t)row * pitch + col0;
; #pragma unroll
;                 for (int bj = 0; bj < 2; ++bj) {
;                     const f32x4 v0 = acc[ai][bj][m][0], v1 = acc[ai][bj][m][1];
;                     const float a0 = (v0[0] * t0[0] - v0[1] * t0[1]) * rs, a1 = (v0[1] * t0[0] + v0[0] * t0[1]) * rs;
;                     const float a2 = (v0[2] * t0[2] - v0[3] * t0[3]) * rs, a3 = (v0[3] * t0[2] + v0[2] * t0[3]) * rs;
;                     const float b0 = (v1[0] * t1[0] - v1[1] * t1[1]) * rs, b1 = (v1[1] * t1[0] + v1[0] * t1[1]) * rs;
;                     const float b2 = (v1[2] * t1[2] - v1[3] * t1[3]) * rs, b3 = (v1[3] * t1[2] + v1[2] * t1[3]) * rs;
;                     u32x4 w; w.x = cvt_pk_bf16(a0, a1); w.y = cvt_pk_bf16(a2, a3); w.z = cvt_pk_bf16(b0, b1); w.w = cvt_pk_bf16(b2, b3);
;                     *(GAS u32x4*)(rowp + bj * 128) = w;
	v_pk_mul_f32 v[154:155], v[108:109], v[188:189]
	v_mov_b32_e32 v121, v194
	v_pk_mul_f32 v[126:127], v[110:111], v[190:191]
	v_pk_mul_f32 v[108:109], v[108:109], v[188:189] op_sel:[1,0] op_sel_hi:[0,1]
	v_pk_mul_f32 v[110:111], v[110:111], v[190:191] op_sel:[1,0] op_sel_hi:[0,1]
	v_pk_mul_f32 v[156:157], v[104:105], v[192:193]
	v_pk_mul_f32 v[104:105], v[104:105], v[192:193] op_sel:[1,0] op_sel_hi:[0,1]
	v_pk_mul_f32 v[158:159], v[106:107], v[194:195] op_sel:[1,0] op_sel_hi:[0,1]
	v_pk_mul_f32 v[160:161], v[102:103], v[190:191]
	v_pk_mul_f32 v[162:163], v[100:101], v[188:189]
	v_pk_mul_f32 v[100:101], v[100:101], v[188:189] op_sel:[1,0] op_sel_hi:[0,1]
	v_pk_mul_f32 v[102:103], v[102:103], v[190:191] op_sel:[1,0] op_sel_hi:[0,1]
	v_pk_mul_f32 v[112:113], v[98:99], v[194:195]
	v_pk_mul_f32 v[114:115], v[96:97], v[192:193]
	v_pk_mul_f32 v[96:97], v[96:97], v[192:193] op_sel:[1,0] op_sel_hi:[0,1]
	v_pk_mul_f32 v[98:99], v[98:99], v[194:195] op_sel:[1,0] op_sel_hi:[0,1]
	s_waitcnt lgkmcnt(0)
	v_pk_mul_f32 v[116:117], v[142:143], v[120:121]
	v_sub_f32_e32 v106, v154, v155
	v_add_f32_e32 v108, v108, v109
	v_sub_f32_e32 v109, v126, v127
	v_add_f32_e32 v110, v110, v111
	v_sub_f32_e32 v111, v156, v157
	v_add_f32_e32 v104, v104, v105
	v_add_f32_e32 v105, v158, v159
	v_add_f32_e32 v96, v96, v97
	v_sub_f32_e32 v97, v112, v113
	v_add_f32_e32 v98, v98, v99
	v_mul_f32_e32 v99, v116, v106
	v_fma_f32 v107, -v107, v195, v117
	v_sub_f32_e32 v118, v162, v163
	v_add_f32_e32 v100, v100, v101
	v_sub_f32_e32 v101, v160, v161
	v_add_f32_e32 v102, v102, v103
	v_sub_f32_e32 v103, v114, v115
	v_mul_f32_e32 v106, v116, v108
	v_mul_f32_e32 v108, v116, v109
	v_mul_f32_e32 v109, v116, v110
	v_mul_f32_e32 v110, v116, v111
	v_mul_f32_e32 v104, v116, v104
	v_mul_f32_e32 v105, v116, v105
	v_mul_f32_e32 v112, v116, v96
	v_mul_f32_e32 v113, v116, v97
	v_mul_f32_e32 v114, v116, v98
	v_mul_f32_e32 v107, v116, v107
	v_cvt_pk_bf16_f32 v96, v99, v106
	v_cvt_pk_bf16_f32 v97, v108, v109
	v_cvt_pk_bf16_f32 v98, v110, v104
	v_cvt_pk_bf16_f32 v99, v107, v105
	v_mul_f32_e32 v111, v116, v118
	v_mul_f32_e32 v100, v116, v100
	v_mul_f32_e32 v101, v116, v101
	v_mul_f32_e32 v102, v116, v102
	v_mul_f32_e32 v103, v116, v103
	global_store_dwordx4 v[124:125], v[96:99], off
	v_pk_mov_b32 v[104:105], v[90:91], v[90:91] op_sel:[1,0]
	v_bitop3_b32 v106, v152, s13, 48 bitop3:0xc8
	v_cvt_pk_bf16_f32 v96, v111, v100
	v_cvt_pk_bf16_f32 v97, v101, v102
	v_cvt_pk_bf16_f32 v98, v103, v112
	v_cvt_pk_bf16_f32 v99, v113, v114
	global_store_dwordx4 v[124:125], v[96:99], off offset:256
	v_add_u32_e32 v222, 0xa0, v152
	v_and_b32_e32 v222, s13, v222
	v_lshlrev_b32_e32 v222, 8, v222
	v_lshl_add_u64 v[178:179], v[136:137], 0, v[222:223]
	global_load_dwordx4 v[188:191], v[178:179], off
	global_load_dwordx4 v[192:195], v[178:179], off offset:16
	s_nop 0
	v_or_b32_e32 v104, 32, v152
	v_lshlrev_b32_e32 v220, 8, v106
	v_mad_i64_i32 v[106:107], s[28:29], s19, v104, 0
	ds_read_b32 v104, v151 offset:128
	v_mov_b32_e32 v143, v105
	v_lshl_add_u64 v[106:107], v[106:107], 1, v[144:145]
	v_lshl_add_u64 v[108:109], v[136:137], 0, v[220:221]
	s_waitcnt vmcnt(12)
	v_pk_mul_f32 v[112:113], v[92:93], v[196:197]
	v_mov_b32_e32 v105, v202
	v_pk_mul_f32 v[110:111], v[94:95], v[198:199]
	v_pk_mul_f32 v[92:93], v[92:93], v[196:197] op_sel:[1,0] op_sel_hi:[0,1]
	v_pk_mul_f32 v[94:95], v[94:95], v[198:199] op_sel:[1,0] op_sel_hi:[0,1]
	v_pk_mul_f32 v[114:115], v[88:89], v[200:201]
	v_pk_mul_f32 v[88:89], v[88:89], v[200:201] op_sel:[1,0] op_sel_hi:[0,1]
	v_pk_mul_f32 v[116:117], v[90:91], v[202:203] op_sel:[1,0] op_sel_hi:[0,1]
	v_pk_mul_f32 v[118:119], v[86:87], v[198:199]
	v_pk_mul_f32 v[120:121], v[84:85], v[196:197]
	v_pk_mul_f32 v[84:85], v[84:85], v[196:197] op_sel:[1,0] op_sel_hi:[0,1]
	v_pk_mul_f32 v[86:87], v[86:87], v[198:199] op_sel:[1,0] op_sel_hi:[0,1]
	v_pk_mul_f32 v[96:97], v[82:83], v[202:203]
	v_pk_mul_f32 v[98:99], v[80:81], v[200:201]
	v_pk_mul_f32 v[80:81], v[80:81], v[200:201] op_sel:[1,0] op_sel_hi:[0,1]
	v_pk_mul_f32 v[82:83], v[82:83], v[202:203] op_sel:[1,0] op_sel_hi:[0,1]
	s_waitcnt lgkmcnt(0)
	v_pk_mul_f32 v[100:101], v[142:143], v[104:105]
	v_sub_f32_e32 v90, v112, v113
	v_add_f32_e32 v92, v92, v93
	v_sub_f32_e32 v93, v110, v111
	v_add_f32_e32 v94, v94, v95
	v_sub_f32_e32 v95, v114, v115
	v_add_f32_e32 v88, v88, v89
	v_add_f32_e32 v89, v116, v117
	v_add_f32_e32 v80, v80, v81
	v_sub_f32_e32 v81, v96, v97
	v_add_f32_e32 v82, v82, v83
	v_mul_f32_e32 v83, v100, v90
	v_fma_f32 v91, -v91, v203, v101
	v_sub_f32_e32 v102, v120, v121
	v_add_f32_e32 v84, v84, v85
	v_sub_f32_e32 v85, v118, v119
	v_add_f32_e32 v86, v86, v87
	v_sub_f32_e32 v87, v98, v99
	v_mul_f32_e32 v90, v100, v92
	v_mul_f32_e32 v92, v100, v93
	v_mul_f32_e32 v93, v100, v94
	v_mul_f32_e32 v94, v100, v95
	v_mul_f32_e32 v88, v100, v88
	v_mul_f32_e32 v89, v100, v89
	v_mul_f32_e32 v96, v100, v80
	v_mul_f32_e32 v97, v100, v81
	v_mul_f32_e32 v98, v100, v82
	v_mul_f32_e32 v91, v100, v91
	v_cvt_pk_bf16_f32 v80, v83, v90
	v_cvt_pk_bf16_f32 v81, v92, v93
	v_cvt_pk_bf16_f32 v82, v94, v88
	v_cvt_pk_bf16_f32 v83, v91, v89
	v_mul_f32_e32 v95, v100, v102
	v_mul_f32_e32 v84, v100, v84
	v_mul_f32_e32 v85, v100, v85
	v_mul_f32_e32 v86, v100, v86
	v_mul_f32_e32 v87, v100, v87
	global_store_dwordx4 v[106:107], v[80:83], off
	v_pk_mov_b32 v[88:89], v[74:75], v[74:75] op_sel:[1,0]
	s_nop 0
	v_cvt_pk_bf16_f32 v80, v95, v84
	v_cvt_pk_bf16_f32 v81, v85, v86
	v_cvt_pk_bf16_f32 v82, v87, v96
	v_cvt_pk_bf16_f32 v83, v97, v98
	global_store_dwordx4 v[106:107], v[80:83], off offset:256
	v_add_u32_e32 v222, 0xb0, v152
	v_and_b32_e32 v222, s13, v222
	v_lshlrev_b32_e32 v222, 8, v222
	v_lshl_add_u64 v[178:179], v[136:137], 0, v[222:223]
	global_load_dwordx4 v[196:199], v[178:179], off
	global_load_dwordx4 v[200:203], v[178:179], off offset:16
	s_nop 0
	v_or_b32_e32 v88, 48, v152
	v_mad_i64_i32 v[90:91], s[28:29], s19, v88, 0
	ds_read_b32 v88, v151 offset:192
	v_mov_b32_e32 v143, v89
	v_add_u32_e32 v106, 0x80, v152
	v_and_b32_e32 v92, s13, v106
	v_lshl_add_u64 v[90:91], v[90:91], 1, v[144:145]
	v_lshlrev_b32_e32 v220, 8, v92
	v_lshl_add_u64 v[92:93], v[136:137], 0, v[220:221]
	s_waitcnt vmcnt(14)
; __device__ __forceinline__ unsigned cvt_pk_bf16(float lo, float hi) { unsigned r; asm volatile("v_cvt_pk_bf16_f32 %0, %1, %2" : "=v"(r) : "v"(lo), "v"(hi)); return r; }
; #define GAS __attribute__((address_space(1)))
;     __device__ __forceinline__ void operator()(const f32x4 (&acc)[2][2][4][2], const Unit& u, int wr, int wc, int fr, int fq) const {
;     ...
;                 const int row = row0 + ai * 128 + m * 16;
;                 const float rs = rsl[u.ord * 256 + wr * 64 + fr + ai * 128 + m * 16] * qs;
;                 const int pos = row & smask;
;                 const f32x4 t0 = *(const GAS f32x4*)(rope + pos * 16 + ub), t1 = *(const GAS f32x4*)(rope + pos * 16 + ub + 1);
;                 bf16_t* rowp = base + (size_t)row * pitch + col0;
; #pragma unroll
;                 for (int bj = 0; bj < 2; ++bj) {
;                     const f32x4 v0 = acc[ai][bj][m][0], v1 = acc[ai][bj][m][1];
;                     const float a0 = (v0[0] * t0[0] - v0[1] * t0[1]) * rs, a1 = (v0[1] * t0[0] + v0[0] * t0[1]) * rs;
;                     const float a2 = (v0[2] * t0[2] - v0[3] * t0[3]) * rs, a3 = (v0[3] * t0[2] + v0[2] * t0[3]) * rs;
;                     const float b0 = (v1[0] * t1[0] - v1[1] * t1[1]) * rs, b1 = (v1[1] * t1[0] + v1[0] * t1[1]) * rs;
;                     const float b2 = (v1[2] * t1[2] - v1[3] * t1[3]) * rs, b3 = (v1[3] * t1[2] + v1[2] * t1[3]) * rs;
;                     u32x4 w; w.x = cvt_pk_bf16(a0, a1); w.y = cvt_pk_bf16(a2, a3); w.z = cvt_pk_bf16(b0, b1); w.w = cvt_pk_bf16(b2, b3);
;                     *(GAS u32x4*)(rowp + bj * 128) = w;
	v_pk_mul_f32 v[96:97], v[76:77], v[204:205]
	v_mov_b32_e32 v89, v210
	v_pk_mul_f32 v[94:95], v[78:79], v[206:207]
	v_pk_mul_f32 v[76:77], v[76:77], v[204:205] op_sel:[1,0] op_sel_hi:[0,1]
	v_pk_mul_f32 v[78:79], v[78:79], v[206:207] op_sel:[1,0] op_sel_hi:[0,1]
	v_pk_mul_f32 v[98:99], v[72:73], v[208:209]
	v_pk_mul_f32 v[72:73], v[72:73], v[208:209] op_sel:[1,0] op_sel_hi:[0,1]
	v_pk_mul_f32 v[100:101], v[74:75], v[210:211] op_sel:[1,0] op_sel_hi:[0,1]
	v_pk_mul_f32 v[102:103], v[70:71], v[206:207]
	v_pk_mul_f32 v[104:105], v[68:69], v[204:205]
	v_pk_mul_f32 v[68:69], v[68:69], v[204:205] op_sel:[1,0] op_sel_hi:[0,1]
	v_pk_mul_f32 v[70:71], v[70:71], v[206:207] op_sel:[1,0] op_sel_hi:[0,1]
	v_pk_mul_f32 v[80:81], v[66:67], v[210:211]
	v_pk_mul_f32 v[82:83], v[64:65], v[208:209]
	v_pk_mul_f32 v[64:65], v[64:65], v[208:209] op_sel:[1,0] op_sel_hi:[0,1]
	v_pk_mul_f32 v[66:67], v[66:67], v[210:211] op_sel:[1,0] op_sel_hi:[0,1]
	s_waitcnt lgkmcnt(0)
	v_pk_mul_f32 v[84:85], v[142:143], v[88:89]
	v_sub_f32_e32 v74, v96, v97
	v_add_f32_e32 v76, v76, v77
	v_sub_f32_e32 v77, v94, v95
	v_add_f32_e32 v78, v78, v79
	v_sub_f32_e32 v79, v98, v99
	v_add_f32_e32 v72, v72, v73
	v_add_f32_e32 v73, v100, v101
	v_add_f32_e32 v64, v64, v65
	v_sub_f32_e32 v65, v80, v81
	v_add_f32_e32 v66, v66, v67
	v_mul_f32_e32 v67, v84, v74
	v_fma_f32 v75, -v75, v211, v85
	v_sub_f32_e32 v86, v104, v105
	v_add_f32_e32 v68, v68, v69
	v_sub_f32_e32 v69, v102, v103
	v_add_f32_e32 v70, v70, v71
	v_sub_f32_e32 v71, v82, v83
	v_mul_f32_e32 v74, v84, v76
	v_mul_f32_e32 v76, v84, v77
	v_mul_f32_e32 v77, v84, v78
	v_mul_f32_e32 v78, v84, v79
	v_mul_f32_e32 v72, v84, v72
	v_mul_f32_e32 v73, v84, v73
	v_mul_f32_e32 v80, v84, v64
	v_mul_f32_e32 v81, v84, v65
	v_mul_f32_e32 v82, v84, v66
	v_mul_f32_e32 v75, v84, v75
	v_cvt_pk_bf16_f32 v64, v67, v74
	v_cvt_pk_bf16_f32 v65, v76, v77
	v_cvt_pk_bf16_f32 v66, v78, v72
	v_cvt_pk_bf16_f32 v67, v75, v73
	v_mul_f32_e32 v79, v84, v86
	v_mul_f32_e32 v68, v84, v68
	v_mul_f32_e32 v69, v84, v69
	v_mul_f32_e32 v70, v84, v70
	v_mul_f32_e32 v71, v84, v71
	global_store_dwordx4 v[90:91], v[64:67], off
	v_pk_mov_b32 v[72:73], v[58:59], v[58:59] op_sel:[1,0]
	v_mad_i64_i32 v[74:75], s[28:29], s19, v106, 0
	v_cvt_pk_bf16_f32 v64, v79, v68
	v_cvt_pk_bf16_f32 v65, v69, v70
	v_cvt_pk_bf16_f32 v66, v71, v80
	v_cvt_pk_bf16_f32 v67, v81, v82
	global_store_dwordx4 v[90:91], v[64:67], off offset:256
	v_add_u32_e32 v90, 0x90, v152
	v_and_b32_e32 v72, s13, v90
	v_lshlrev_b32_e32 v220, 8, v72
	ds_read_b32 v72, v151 offset:512
	v_mov_b32_e32 v143, v73
	v_lshl_add_u64 v[74:75], v[74:75], 1, v[144:145]
	v_lshl_add_u64 v[76:77], v[136:137], 0, v[220:221]
	s_waitcnt vmcnt(14)
	v_pk_mul_f32 v[80:81], v[60:61], v[212:213]
	v_mov_b32_e32 v73, v218
	v_pk_mul_f32 v[78:79], v[62:63], v[214:215]
	v_pk_mul_f32 v[60:61], v[60:61], v[212:213] op_sel:[1,0] op_sel_hi:[0,1]
	v_pk_mul_f32 v[62:63], v[62:63], v[214:215] op_sel:[1,0] op_sel_hi:[0,1]
	v_pk_mul_f32 v[82:83], v[56:57], v[216:217]
	v_pk_mul_f32 v[56:57], v[56:57], v[216:217] op_sel:[1,0] op_sel_hi:[0,1]
	v_pk_mul_f32 v[84:85], v[58:59], v[218:219] op_sel:[1,0] op_sel_hi:[0,1]
	v_pk_mul_f32 v[86:87], v[54:55], v[214:215]
	v_pk_mul_f32 v[88:89], v[52:53], v[212:213]
	v_pk_mul_f32 v[52:53], v[52:53], v[212:213] op_sel:[1,0] op_sel_hi:[0,1]
	v_pk_mul_f32 v[54:55], v[54:55], v[214:215] op_sel:[1,0] op_sel_hi:[0,1]
	v_pk_mul_f32 v[64:65], v[50:51], v[218:219]
	v_pk_mul_f32 v[66:67], v[48:49], v[216:217]
	v_pk_mul_f32 v[48:49], v[48:49], v[216:217] op_sel:[1,0] op_sel_hi:[0,1]
	v_pk_mul_f32 v[50:51], v[50:51], v[218:219] op_sel:[1,0] op_sel_hi:[0,1]
	s_waitcnt lgkmcnt(0)
	v_pk_mul_f32 v[68:69], v[142:143], v[72:73]
	v_sub_f32_e32 v58, v80, v81
	v_add_f32_e32 v60, v60, v61
	v_sub_f32_e32 v61, v78, v79
	v_add_f32_e32 v62, v62, v63
	v_sub_f32_e32 v63, v82, v83
	v_add_f32_e32 v56, v56, v57
	v_add_f32_e32 v57, v84, v85
	v_add_f32_e32 v48, v48, v49
	v_sub_f32_e32 v49, v64, v65
	v_add_f32_e32 v50, v50, v51
	v_mul_f32_e32 v51, v68, v58
	v_fma_f32 v59, -v59, v219, v69
	v_sub_f32_e32 v70, v88, v89
	v_add_f32_e32 v52, v52, v53
	v_sub_f32_e32 v53, v86, v87
	v_add_f32_e32 v54, v54, v55
	v_sub_f32_e32 v55, v66, v67
	v_mul_f32_e32 v58, v68, v60
	v_mul_f32_e32 v60, v68, v61
	v_mul_f32_e32 v61, v68, v62
	v_mul_f32_e32 v62, v68, v63
	v_mul_f32_e32 v56, v68, v56
	v_mul_f32_e32 v57, v68, v57
	v_mul_f32_e32 v64, v68, v48
	v_mul_f32_e32 v65, v68, v49
	v_mul_f32_e32 v66, v68, v50
	v_mul_f32_e32 v59, v68, v59
	v_cvt_pk_bf16_f32 v48, v51, v58
	v_cvt_pk_bf16_f32 v49, v60, v61
	v_cvt_pk_bf16_f32 v50, v62, v56
	v_cvt_pk_bf16_f32 v51, v59, v57
	v_mul_f32_e32 v63, v68, v70
	v_mul_f32_e32 v52, v68, v52
	v_mul_f32_e32 v53, v68, v53
	v_mul_f32_e32 v54, v68, v54
	v_mul_f32_e32 v55, v68, v55
	global_store_dwordx4 v[74:75], v[48:51], off
	v_pk_mov_b32 v[56:57], v[42:43], v[42:43] op_sel:[1,0]
	v_mad_i64_i32 v[58:59], s[28:29], s19, v90, 0
	v_cvt_pk_bf16_f32 v48, v63, v52
	v_cvt_pk_bf16_f32 v49, v53, v54
	v_cvt_pk_bf16_f32 v50, v55, v64
	v_cvt_pk_bf16_f32 v51, v65, v66
	global_store_dwordx4 v[74:75], v[48:51], off offset:256
	s_nop 0
	v_add_u32_e32 v74, 0xa0, v152
	v_and_b32_e32 v56, s13, v74
	v_lshlrev_b32_e32 v220, 8, v56
	ds_read_b32 v56, v151 offset:576
	v_mov_b32_e32 v143, v57
	v_lshl_add_u64 v[58:59], v[58:59], 1, v[144:145]
	v_lshl_add_u64 v[60:61], v[136:137], 0, v[220:221]
	s_waitcnt vmcnt(12)
; __device__ __forceinline__ unsigned cvt_pk_bf16(float lo, float hi) { unsigned r; asm volatile("v_cvt_pk_bf16_f32 %0, %1, %2" : "=v"(r) : "v"(lo), "v"(hi)); return r; }
; #define GAS __attribute__((address_space(1)))
;     __device__ __forceinline__ void operator()(const f32x4 (&acc)[2][2][4][2], const Unit& u, int wr, int wc, int fr, int fq) const {
;     ...
;                 const int row = row0 + ai * 128 + m * 16;
;                 const float rs = rsl[u.ord * 256 + wr * 64 + fr + ai * 128 + m * 16] * qs;
;                 const int pos = row & smask;
;                 const f32x4 t0 = *(const GAS f32x4*)(rope + pos * 16 + ub), t1 = *(const GAS f32x4*)(rope + pos * 16 + ub + 1);
;                 bf16_t* rowp = base + (size_t)row * pitch + col0;
; #pragma unroll
;                 for (int bj = 0; bj < 2; ++bj) {
;                     const f32x4 v0 = acc[ai][bj][m][0], v1 = acc[ai][bj][m][1];
;                     const float a0 = (v0[0] * t0[0] - v0[1] * t0[1]) * rs, a1 = (v0[1] * t0[0] + v0[0] * t0[1]) * rs;
;                     const float a2 = (v0[2] * t0[2] - v0[3] * t0[3]) * rs, a3 = (v0[3] * t0[2] + v0[2] * t0[3]) * rs;
;                     const float b0 = (v1[0] * t1[0] - v1[1] * t1[1]) * rs, b1 = (v1[1] * t1[0] + v1[0] * t1[1]) * rs;
;                     const float b2 = (v1[2] * t1[2] - v1[3] * t1[3]) * rs, b3 = (v1[3] * t1[2] + v1[2] * t1[3]) * rs;
;                     u32x4 w; w.x = cvt_pk_bf16(a0, a1); w.y = cvt_pk_bf16(a2, a3); w.z = cvt_pk_bf16(b0, b1); w.w = cvt_pk_bf16(b2, b3);
;                     *(GAS u32x4*)(rowp + bj * 128) = w;
	v_pk_mul_f32 v[64:65], v[44:45], v[180:181]
	v_mov_b32_e32 v57, v186
	v_pk_mul_f32 v[62:63], v[46:47], v[182:183]
	v_pk_mul_f32 v[44:45], v[44:45], v[180:181] op_sel:[1,0] op_sel_hi:[0,1]
	v_pk_mul_f32 v[46:47], v[46:47], v[182:183] op_sel:[1,0] op_sel_hi:[0,1]
	v_pk_mul_f32 v[66:67], v[40:41], v[184:185]
	v_pk_mul_f32 v[40:41], v[40:41], v[184:185] op_sel:[1,0] op_sel_hi:[0,1]
	v_pk_mul_f32 v[68:69], v[42:43], v[186:187] op_sel:[1,0] op_sel_hi:[0,1]
	v_pk_mul_f32 v[70:71], v[38:39], v[182:183]
	v_pk_mul_f32 v[72:73], v[36:37], v[180:181]
	v_pk_mul_f32 v[36:37], v[36:37], v[180:181] op_sel:[1,0] op_sel_hi:[0,1]
	v_pk_mul_f32 v[38:39], v[38:39], v[182:183] op_sel:[1,0] op_sel_hi:[0,1]
	v_pk_mul_f32 v[48:49], v[34:35], v[186:187]
	v_pk_mul_f32 v[50:51], v[32:33], v[184:185]
	v_pk_mul_f32 v[32:33], v[32:33], v[184:185] op_sel:[1,0] op_sel_hi:[0,1]
	v_pk_mul_f32 v[34:35], v[34:35], v[186:187] op_sel:[1,0] op_sel_hi:[0,1]
	s_waitcnt lgkmcnt(0)
	v_pk_mul_f32 v[52:53], v[142:143], v[56:57]
	v_sub_f32_e32 v42, v64, v65
	v_add_f32_e32 v44, v44, v45
	v_sub_f32_e32 v45, v62, v63
	v_add_f32_e32 v46, v46, v47
	v_sub_f32_e32 v47, v66, v67
	v_add_f32_e32 v40, v40, v41
	v_add_f32_e32 v41, v68, v69
	v_add_f32_e32 v32, v32, v33
	v_sub_f32_e32 v33, v48, v49
	v_add_f32_e32 v34, v34, v35
	v_mul_f32_e32 v35, v52, v42
	v_fma_f32 v43, -v43, v187, v53
	v_sub_f32_e32 v54, v72, v73
	v_add_f32_e32 v36, v36, v37
	v_sub_f32_e32 v37, v70, v71
	v_add_f32_e32 v38, v38, v39
	v_sub_f32_e32 v39, v50, v51
	v_mul_f32_e32 v42, v52, v44
	v_mul_f32_e32 v44, v52, v45
	v_mul_f32_e32 v45, v52, v46
	v_mul_f32_e32 v46, v52, v47
	v_mul_f32_e32 v40, v52, v40
	v_mul_f32_e32 v41, v52, v41
	v_mul_f32_e32 v48, v52, v32
	v_mul_f32_e32 v49, v52, v33
	v_mul_f32_e32 v50, v52, v34
	v_mul_f32_e32 v43, v52, v43
	v_cvt_pk_bf16_f32 v32, v35, v42
	v_cvt_pk_bf16_f32 v33, v44, v45
	v_cvt_pk_bf16_f32 v34, v46, v40
	v_cvt_pk_bf16_f32 v35, v43, v41
	v_mul_f32_e32 v47, v52, v54
	v_mul_f32_e32 v36, v52, v36
	v_mul_f32_e32 v37, v52, v37
	v_mul_f32_e32 v38, v52, v38
	v_mul_f32_e32 v39, v52, v39
	global_store_dwordx4 v[58:59], v[32:35], off
	v_pk_mov_b32 v[40:41], v[26:27], v[26:27] op_sel:[1,0]
	v_mad_i64_i32 v[42:43], s[28:29], s19, v74, 0
	v_cvt_pk_bf16_f32 v32, v47, v36
	v_cvt_pk_bf16_f32 v33, v37, v38
	v_cvt_pk_bf16_f32 v34, v39, v48
	v_cvt_pk_bf16_f32 v35, v49, v50
	global_store_dwordx4 v[58:59], v[32:35], off offset:256
	s_nop 0
	v_add_u32_e32 v58, 0xb0, v152
	v_and_b32_e32 v40, s13, v58
	v_lshlrev_b32_e32 v220, 8, v40
	ds_read_b32 v40, v151 offset:640
	v_mov_b32_e32 v143, v41
	v_lshl_add_u64 v[42:43], v[42:43], 1, v[144:145]
	v_lshl_add_u64 v[44:45], v[136:137], 0, v[220:221]
	s_waitcnt vmcnt(10)
	v_pk_mul_f32 v[48:49], v[28:29], v[188:189]
	v_mov_b32_e32 v41, v194
	v_pk_mul_f32 v[46:47], v[30:31], v[190:191]
	v_pk_mul_f32 v[28:29], v[28:29], v[188:189] op_sel:[1,0] op_sel_hi:[0,1]
	v_pk_mul_f32 v[30:31], v[30:31], v[190:191] op_sel:[1,0] op_sel_hi:[0,1]
	v_pk_mul_f32 v[50:51], v[24:25], v[192:193]
	v_pk_mul_f32 v[24:25], v[24:25], v[192:193] op_sel:[1,0] op_sel_hi:[0,1]
	v_pk_mul_f32 v[52:53], v[26:27], v[194:195] op_sel:[1,0] op_sel_hi:[0,1]
	v_pk_mul_f32 v[54:55], v[22:23], v[190:191]
	v_pk_mul_f32 v[56:57], v[20:21], v[188:189]
	v_pk_mul_f32 v[20:21], v[20:21], v[188:189] op_sel:[1,0] op_sel_hi:[0,1]
	v_pk_mul_f32 v[22:23], v[22:23], v[190:191] op_sel:[1,0] op_sel_hi:[0,1]
	v_pk_mul_f32 v[32:33], v[18:19], v[194:195]
	v_pk_mul_f32 v[34:35], v[16:17], v[192:193]
	v_pk_mul_f32 v[16:17], v[16:17], v[192:193] op_sel:[1,0] op_sel_hi:[0,1]
	v_pk_mul_f32 v[18:19], v[18:19], v[194:195] op_sel:[1,0] op_sel_hi:[0,1]
	s_waitcnt lgkmcnt(0)
; __device__ __forceinline__ unsigned cvt_pk_bf16(float lo, float hi) { unsigned r; asm volatile("v_cvt_pk_bf16_f32 %0, %1, %2" : "=v"(r) : "v"(lo), "v"(hi)); return r; }
; #define GAS __attribute__((address_space(1)))
;     __device__ __forceinline__ void operator()(const f32x4 (&acc)[2][2][4][2], const Unit& u, int wr, int wc, int fr, int fq) const {
;     ...
;                 const int row = row0 + ai * 128 + m * 16;
;                 const float rs = rsl[u.ord * 256 + wr * 64 + fr + ai * 128 + m * 16] * qs;
;                 const int pos = row & smask;
;                 const f32x4 t0 = *(const GAS f32x4*)(rope + pos * 16 + ub), t1 = *(const GAS f32x4*)(rope + pos * 16 + ub + 1);
;                 bf16_t* rowp = base + (size_t)row * pitch + col0;
; #pragma unroll
;                 for (int bj = 0; bj < 2; ++bj) {
;                     const f32x4 v0 = acc[ai][bj][m][0], v1 = acc[ai][bj][m][1];
;                     const float a0 = (v0[0] * t0[0] - v0[1] * t0[1]) * rs, a1 = (v0[1] * t0[0] + v0[0] * t0[1]) * rs;
;                     const float a2 = (v0[2] * t0[2] - v0[3] * t0[3]) * rs, a3 = (v0[3] * t0[2] + v0[2] * t0[3]) * rs;
;                     const float b0 = (v1[0] * t1[0] - v1[1] * t1[1]) * rs, b1 = (v1[1] * t1[0] + v1[0] * t1[1]) * rs;
;                     const float b2 = (v1[2] * t1[2] - v1[3] * t1[3]) * rs, b3 = (v1[3] * t1[2] + v1[2] * t1[3]) * rs;
;                     u32x4 w; w.x = cvt_pk_bf16(a0, a1); w.y = cvt_pk_bf16(a2, a3); w.z = cvt_pk_bf16(b0, b1); w.w = cvt_pk_bf16(b2, b3);
;                     *(GAS u32x4*)(rowp + bj * 128) = w;
;                 }
;                 if (m == 3) asm volatile("" ::: "memory");
	v_pk_mul_f32 v[36:37], v[142:143], v[40:41]
	v_sub_f32_e32 v26, v48, v49
	v_add_f32_e32 v28, v28, v29
	v_sub_f32_e32 v29, v46, v47
	v_add_f32_e32 v30, v30, v31
	v_sub_f32_e32 v31, v50, v51
	v_add_f32_e32 v24, v24, v25
	v_add_f32_e32 v25, v52, v53
	v_add_f32_e32 v16, v16, v17
	v_sub_f32_e32 v17, v32, v33
	v_add_f32_e32 v18, v18, v19
	v_mul_f32_e32 v19, v36, v26
	v_fma_f32 v27, -v27, v195, v37
	v_sub_f32_e32 v38, v56, v57
	v_add_f32_e32 v20, v20, v21
	v_sub_f32_e32 v21, v54, v55
	v_add_f32_e32 v22, v22, v23
	v_sub_f32_e32 v23, v34, v35
	v_mul_f32_e32 v26, v36, v28
	v_mul_f32_e32 v28, v36, v29
	v_mul_f32_e32 v29, v36, v30
	v_mul_f32_e32 v30, v36, v31
	v_mul_f32_e32 v24, v36, v24
	v_mul_f32_e32 v25, v36, v25
	v_mul_f32_e32 v32, v36, v16
	v_mul_f32_e32 v33, v36, v17
	v_mul_f32_e32 v34, v36, v18
	v_mul_f32_e32 v27, v36, v27
	v_cvt_pk_bf16_f32 v16, v19, v26
	v_cvt_pk_bf16_f32 v17, v28, v29
	v_cvt_pk_bf16_f32 v18, v30, v24
	v_cvt_pk_bf16_f32 v19, v27, v25
	v_mul_f32_e32 v31, v36, v38
	v_mul_f32_e32 v20, v36, v20
	v_mul_f32_e32 v21, v36, v21
	v_mul_f32_e32 v22, v36, v22
	v_mul_f32_e32 v23, v36, v23
	global_store_dwordx4 v[42:43], v[16:19], off
	v_pk_mov_b32 v[24:25], v[6:7], v[6:7] op_sel:[1,0]
	v_mad_i64_i32 v[26:27], s[28:29], s19, v58, 0
	v_cvt_pk_bf16_f32 v16, v31, v20
	v_cvt_pk_bf16_f32 v17, v21, v22
	v_cvt_pk_bf16_f32 v18, v23, v32
	v_cvt_pk_bf16_f32 v19, v33, v34
	global_store_dwordx4 v[42:43], v[16:19], off offset:256
	s_nop 0
	ds_read_b32 v24, v151 offset:704
	v_mov_b32_e32 v143, v25
	v_lshl_add_u64 v[26:27], v[26:27], 1, v[144:145]
	s_waitcnt vmcnt(8)
	v_pk_mul_f32 v[30:31], v[12:13], v[196:197]
	v_mov_b32_e32 v25, v202
	v_pk_mul_f32 v[28:29], v[14:15], v[198:199]
	v_pk_mul_f32 v[12:13], v[12:13], v[196:197] op_sel:[1,0] op_sel_hi:[0,1]
	v_pk_mul_f32 v[14:15], v[14:15], v[198:199] op_sel:[1,0] op_sel_hi:[0,1]
	v_pk_mul_f32 v[32:33], v[4:5], v[200:201]
	v_pk_mul_f32 v[4:5], v[4:5], v[200:201] op_sel:[1,0] op_sel_hi:[0,1]
	v_pk_mul_f32 v[34:35], v[6:7], v[202:203] op_sel:[1,0] op_sel_hi:[0,1]
	v_pk_mul_f32 v[36:37], v[10:11], v[198:199]
	v_pk_mul_f32 v[38:39], v[8:9], v[196:197]
	v_pk_mul_f32 v[8:9], v[8:9], v[196:197] op_sel:[1,0] op_sel_hi:[0,1]
	v_pk_mul_f32 v[10:11], v[10:11], v[198:199] op_sel:[1,0] op_sel_hi:[0,1]
	v_pk_mul_f32 v[16:17], v[2:3], v[202:203]
	v_pk_mul_f32 v[18:19], v[0:1], v[200:201]
	v_pk_mul_f32 v[0:1], v[0:1], v[200:201] op_sel:[1,0] op_sel_hi:[0,1]
	v_pk_mul_f32 v[2:3], v[2:3], v[202:203] op_sel:[1,0] op_sel_hi:[0,1]
	s_waitcnt lgkmcnt(0)
	v_pk_mul_f32 v[20:21], v[142:143], v[24:25]
	v_sub_f32_e32 v6, v30, v31
	v_add_f32_e32 v12, v12, v13
	v_sub_f32_e32 v13, v28, v29
	v_add_f32_e32 v14, v14, v15
	v_sub_f32_e32 v15, v32, v33
	v_add_f32_e32 v4, v4, v5
	v_add_f32_e32 v5, v34, v35
	v_add_f32_e32 v0, v0, v1
	v_sub_f32_e32 v1, v16, v17
	v_add_f32_e32 v2, v2, v3
	v_mul_f32_e32 v3, v20, v6
	v_fma_f32 v7, -v7, v203, v21
	v_sub_f32_e32 v22, v38, v39
	v_add_f32_e32 v8, v8, v9
	v_sub_f32_e32 v9, v36, v37
	v_add_f32_e32 v10, v10, v11
	v_sub_f32_e32 v11, v18, v19
	v_mul_f32_e32 v6, v20, v12
	v_mul_f32_e32 v12, v20, v13
	v_mul_f32_e32 v13, v20, v14
	v_mul_f32_e32 v14, v20, v15
	v_mul_f32_e32 v4, v20, v4
	v_mul_f32_e32 v5, v20, v5
	v_mul_f32_e32 v16, v20, v0
	v_mul_f32_e32 v17, v20, v1
	v_mul_f32_e32 v18, v20, v2
	v_mul_f32_e32 v7, v20, v7
	v_cvt_pk_bf16_f32 v0, v3, v6
	v_cvt_pk_bf16_f32 v1, v12, v13
	v_cvt_pk_bf16_f32 v2, v14, v4
	v_cvt_pk_bf16_f32 v3, v7, v5
	v_mul_f32_e32 v15, v20, v22
	v_mul_f32_e32 v8, v20, v8
	v_mul_f32_e32 v9, v20, v9
	v_mul_f32_e32 v10, v20, v10
	v_mul_f32_e32 v11, v20, v11
	global_store_dwordx4 v[26:27], v[0:3], off
	s_nop 1
	v_cvt_pk_bf16_f32 v0, v15, v8
	v_cvt_pk_bf16_f32 v1, v9, v10
	v_cvt_pk_bf16_f32 v2, v11, v16
	v_cvt_pk_bf16_f32 v3, v17, v18
	global_store_dwordx4 v[26:27], v[0:3], off offset:256
	s_cbranch_vccnz .LBB0_368
	s_andn2_b64 vcc, exec, s[14:15]
	s_cbranch_vccnz .LBB0_367
	s_barrier
	s_branch .LBB0_367
